# P6 SwiGLU epilogue algebra: rcp(q+q*e) with q=ssq/1024+eps replaces r^2*rcp(1+e): 40 fewer VALU ops per wave-tile
# speedup vs baseline: 1.0075x; 1.0075x over previous
.LBB0_690:
	v_fmamk_f32 v144, v166, 0x3a800000, v151
	v_mov_b32_e32 v200, v144
	v_rsq_f32_e32 v145, v144
	v_pk_mul_f32 v[120:121], v[124:125], v[120:121]
	v_pk_mul_f32 v[122:123], v[126:127], v[122:123]
	v_pk_mul_f32 v[112:113], v[116:117], v[112:113]
	v_mul_f32_e32 v166, 0xbfb8aa3b, v145
	v_pk_mul_f32 v[168:169], v[166:167], v[124:125] op_sel_hi:[0,1]
	v_exp_f32_e32 v168, v168
	v_exp_f32_e32 v169, v169
	v_pk_mul_f32 v[124:125], v[166:167], v[126:127] op_sel_hi:[0,1]
	v_exp_f32_e32 v124, v124
	v_exp_f32_e32 v125, v125
	v_pk_fma_f32 v[168:169], v[168:169], v[200:201], v[200:201] op_sel_hi:[1,0,0]
	v_rcp_f32_e32 v168, v168
	v_rcp_f32_e32 v169, v169
	v_pk_fma_f32 v[124:125], v[124:125], v[200:201], v[200:201] op_sel_hi:[1,0,0]
	v_pk_mul_f32 v[114:115], v[118:119], v[114:115]
	v_rcp_f32_e32 v124, v124
	v_rcp_f32_e32 v125, v125
	v_pk_mul_f32 v[120:121], v[168:169], v[120:121]
	v_pk_mul_f32 v[126:127], v[166:167], v[116:117] op_sel_hi:[0,1]
	v_exp_f32_e32 v126, v126
	v_exp_f32_e32 v127, v127
	v_pk_mul_f32 v[122:123], v[124:125], v[122:123]
	v_pk_mul_f32 v[124:125], v[166:167], v[118:119] op_sel_hi:[0,1]
	v_exp_f32_e32 v124, v124
	v_exp_f32_e32 v125, v125
	v_cvt_pk_bf16_f32 v120, v120, v121
	v_cvt_pk_bf16_f32 v121, v122, v123
	v_pk_fma_f32 v[122:123], v[126:127], v[200:201], v[200:201] op_sel_hi:[1,0,0]
	v_pk_fma_f32 v[116:117], v[124:125], v[200:201], v[200:201] op_sel_hi:[1,0,0]
	v_rcp_f32_e32 v122, v122
	v_rcp_f32_e32 v123, v123
	v_rcp_f32_e32 v116, v116
	v_rcp_f32_e32 v117, v117
	v_lshl_or_b32 v170, s18, 7, v148
	v_pk_mul_f32 v[112:113], v[122:123], v[112:113]
	v_lshl_add_u32 v144, s36, 8, v146
	v_cvt_pk_bf16_f32 v122, v112, v113
	v_pk_mul_f32 v[112:113], v[116:117], v[114:115]
	v_fmamk_f32 v114, v165, 0x3a800000, v151
	v_mov_b32_e32 v202, v114
	v_rsq_f32_e32 v119, v114
	v_ashrrev_i32_e32 v171, 31, v170
	v_cvt_pk_bf16_f32 v123, v112, v113
	v_mov_b64_e32 v[112:113], s[34:35]
	v_mul_f32_e32 v118, 0xbfb8aa3b, v119
	v_pk_mul_f32 v[124:125], v[118:119], v[108:109] op_sel_hi:[0,1]
	v_exp_f32_e32 v124, v124
	v_exp_f32_e32 v125, v125
	v_pk_mul_f32 v[104:105], v[108:109], v[104:105]
	v_pk_mul_f32 v[108:109], v[118:119], v[110:111] op_sel_hi:[0,1]
	v_mad_i64_i32 v[116:117], s[18:19], v144, s56, v[112:113]
	v_lshlrev_b64 v[114:115], 1, v[170:171]
	v_exp_f32_e32 v108, v108
	v_exp_f32_e32 v109, v109
	v_lshl_add_u64 v[116:117], v[116:117], 0, v[114:115]
	global_store_dwordx4 v[116:117], v[120:123], off
	s_nop 0
	v_pk_fma_f32 v[108:109], v[108:109], v[202:203], v[202:203] op_sel_hi:[1,0,0]
	v_pk_fma_f32 v[120:121], v[124:125], v[202:203], v[202:203] op_sel_hi:[1,0,0]
	v_rcp_f32_e32 v108, v108
	v_rcp_f32_e32 v120, v120
	v_rcp_f32_e32 v121, v121
	v_rcp_f32_e32 v109, v109
	v_pk_mul_f32 v[106:107], v[110:111], v[106:107]
	v_pk_mul_f32 v[96:97], v[100:101], v[96:97]
	v_pk_mul_f32 v[104:105], v[120:121], v[104:105]
	v_pk_mul_f32 v[110:111], v[118:119], v[100:101] op_sel_hi:[0,1]
	v_exp_f32_e32 v110, v110
	v_exp_f32_e32 v111, v111
	v_pk_mul_f32 v[106:107], v[108:109], v[106:107]
	v_pk_mul_f32 v[108:109], v[118:119], v[102:103] op_sel_hi:[0,1]
	v_exp_f32_e32 v108, v108
	v_exp_f32_e32 v109, v109
	v_cvt_pk_bf16_f32 v104, v104, v105
	v_cvt_pk_bf16_f32 v105, v106, v107
	v_pk_fma_f32 v[106:107], v[110:111], v[202:203], v[202:203] op_sel_hi:[1,0,0]
	v_pk_fma_f32 v[100:101], v[108:109], v[202:203], v[202:203] op_sel_hi:[1,0,0]
	v_rcp_f32_e32 v106, v106
	v_rcp_f32_e32 v107, v107
	v_rcp_f32_e32 v100, v100
	v_rcp_f32_e32 v101, v101
	v_pk_mul_f32 v[98:99], v[102:103], v[98:99]
	v_pk_mul_f32 v[96:97], v[106:107], v[96:97]
	v_pk_mul_f32 v[88:89], v[92:93], v[88:89]
	v_cvt_pk_bf16_f32 v106, v96, v97
	v_pk_mul_f32 v[96:97], v[100:101], v[98:99]
	v_pk_mul_f32 v[90:91], v[94:95], v[90:91]
	v_cvt_pk_bf16_f32 v107, v96, v97
	v_fmamk_f32 v96, v164, 0x3a800000, v151
	v_mov_b32_e32 v204, v96
	v_rsq_f32_e32 v99, v96
	v_or_b32_e32 v96, 16, v144
	v_mad_i64_i32 v[96:97], s[18:19], v96, s56, v[112:113]
	v_mul_f32_e32 v98, 0xbfb8aa3b, v99
	v_pk_mul_f32 v[100:101], v[98:99], v[92:93] op_sel_hi:[0,1]
	v_exp_f32_e32 v100, v100
	v_exp_f32_e32 v101, v101
	v_pk_mul_f32 v[92:93], v[98:99], v[94:95] op_sel_hi:[0,1]
	v_exp_f32_e32 v92, v92
	v_exp_f32_e32 v93, v93
	v_pk_fma_f32 v[100:101], v[100:101], v[204:205], v[204:205] op_sel_hi:[1,0,0]
	v_lshl_add_u64 v[96:97], v[96:97], 0, v[114:115]
	v_rcp_f32_e32 v100, v100
	v_rcp_f32_e32 v101, v101
	v_pk_fma_f32 v[92:93], v[92:93], v[204:205], v[204:205] op_sel_hi:[1,0,0]
	global_store_dwordx4 v[96:97], v[104:107], off
	v_rcp_f32_e32 v92, v92
	v_rcp_f32_e32 v93, v93
	v_pk_mul_f32 v[88:89], v[100:101], v[88:89]
	v_pk_mul_f32 v[94:95], v[98:99], v[84:85] op_sel_hi:[0,1]
	v_exp_f32_e32 v94, v94
	v_exp_f32_e32 v95, v95
	v_pk_mul_f32 v[90:91], v[92:93], v[90:91]
	v_pk_mul_f32 v[92:93], v[98:99], v[86:87] op_sel_hi:[0,1]
	v_exp_f32_e32 v92, v92
	v_exp_f32_e32 v93, v93
	v_cvt_pk_bf16_f32 v88, v88, v89
	v_cvt_pk_bf16_f32 v89, v90, v91
	v_pk_fma_f32 v[90:91], v[94:95], v[204:205], v[204:205] op_sel_hi:[1,0,0]
	v_pk_mul_f32 v[80:81], v[84:85], v[80:81]
	v_rcp_f32_e32 v90, v90
	v_rcp_f32_e32 v91, v91
	v_pk_fma_f32 v[84:85], v[92:93], v[204:205], v[204:205] op_sel_hi:[1,0,0]
	v_pk_mul_f32 v[82:83], v[86:87], v[82:83]
	v_rcp_f32_e32 v84, v84
	v_rcp_f32_e32 v85, v85
	v_pk_mul_f32 v[80:81], v[90:91], v[80:81]
	v_pk_mul_f32 v[72:73], v[76:77], v[72:73]
	v_cvt_pk_bf16_f32 v90, v80, v81
	v_pk_mul_f32 v[80:81], v[84:85], v[82:83]
	v_pk_mul_f32 v[74:75], v[78:79], v[74:75]
	v_cvt_pk_bf16_f32 v91, v80, v81
	v_fmamk_f32 v80, v163, 0x3a800000, v151
	v_mov_b32_e32 v206, v80
	v_rsq_f32_e32 v83, v80
	v_or_b32_e32 v80, 32, v144
	v_mad_i64_i32 v[80:81], s[18:19], v80, s56, v[112:113]
	v_mul_f32_e32 v82, 0xbfb8aa3b, v83
	v_pk_mul_f32 v[84:85], v[82:83], v[76:77] op_sel_hi:[0,1]
	v_exp_f32_e32 v84, v84
	v_exp_f32_e32 v85, v85
	v_pk_mul_f32 v[76:77], v[82:83], v[78:79] op_sel_hi:[0,1]
	v_exp_f32_e32 v76, v76
	v_exp_f32_e32 v77, v77
	v_pk_fma_f32 v[84:85], v[84:85], v[206:207], v[206:207] op_sel_hi:[1,0,0]
	v_lshl_add_u64 v[80:81], v[80:81], 0, v[114:115]
	v_rcp_f32_e32 v84, v84
	v_rcp_f32_e32 v85, v85
	v_pk_fma_f32 v[76:77], v[76:77], v[206:207], v[206:207] op_sel_hi:[1,0,0]
	global_store_dwordx4 v[80:81], v[88:91], off
	v_rcp_f32_e32 v76, v76
	v_rcp_f32_e32 v77, v77
	v_pk_mul_f32 v[72:73], v[84:85], v[72:73]
	v_pk_mul_f32 v[78:79], v[82:83], v[68:69] op_sel_hi:[0,1]
	v_exp_f32_e32 v78, v78
	v_exp_f32_e32 v79, v79
	v_pk_mul_f32 v[74:75], v[76:77], v[74:75]
	v_pk_mul_f32 v[76:77], v[82:83], v[70:71] op_sel_hi:[0,1]
	v_exp_f32_e32 v76, v76
	v_exp_f32_e32 v77, v77
	v_cvt_pk_bf16_f32 v72, v72, v73
	v_cvt_pk_bf16_f32 v73, v74, v75
	v_pk_fma_f32 v[74:75], v[78:79], v[206:207], v[206:207] op_sel_hi:[1,0,0]
	v_pk_mul_f32 v[64:65], v[68:69], v[64:65]
	v_rcp_f32_e32 v74, v74
	v_rcp_f32_e32 v75, v75
	v_pk_fma_f32 v[68:69], v[76:77], v[206:207], v[206:207] op_sel_hi:[1,0,0]
	v_pk_mul_f32 v[66:67], v[70:71], v[66:67]
	v_rcp_f32_e32 v68, v68
	v_rcp_f32_e32 v69, v69
	v_pk_mul_f32 v[64:65], v[74:75], v[64:65]
	v_pk_mul_f32 v[56:57], v[60:61], v[56:57]
	v_cvt_pk_bf16_f32 v74, v64, v65
	v_pk_mul_f32 v[64:65], v[68:69], v[66:67]
	v_pk_mul_f32 v[58:59], v[62:63], v[58:59]
	v_cvt_pk_bf16_f32 v75, v64, v65
	v_fmamk_f32 v65, v162, 0x3a800000, v151
	v_mov_b32_e32 v208, v65
	v_rsq_f32_e32 v67, v65
	v_or_b32_e32 v64, 48, v144
	v_mad_i64_i32 v[64:65], s[18:19], v64, s56, v[112:113]
	v_mul_f32_e32 v66, 0xbfb8aa3b, v67
	v_pk_mul_f32 v[68:69], v[66:67], v[60:61] op_sel_hi:[0,1]
	v_exp_f32_e32 v68, v68
	v_exp_f32_e32 v69, v69
	v_pk_mul_f32 v[60:61], v[66:67], v[62:63] op_sel_hi:[0,1]
	v_exp_f32_e32 v60, v60
	v_exp_f32_e32 v61, v61
	v_pk_fma_f32 v[68:69], v[68:69], v[208:209], v[208:209] op_sel_hi:[1,0,0]
	v_lshl_add_u64 v[64:65], v[64:65], 0, v[114:115]
	v_rcp_f32_e32 v68, v68
	v_rcp_f32_e32 v69, v69
	v_pk_fma_f32 v[60:61], v[60:61], v[208:209], v[208:209] op_sel_hi:[1,0,0]
	global_store_dwordx4 v[64:65], v[72:75], off
	v_rcp_f32_e32 v60, v60
	v_rcp_f32_e32 v61, v61
	v_add_u32_e32 v65, 0x80, v144
	v_pk_mul_f32 v[56:57], v[68:69], v[56:57]
	v_pk_mul_f32 v[62:63], v[66:67], v[52:53] op_sel_hi:[0,1]
	v_exp_f32_e32 v62, v62
	v_exp_f32_e32 v63, v63
	v_pk_mul_f32 v[58:59], v[60:61], v[58:59]
	v_pk_mul_f32 v[60:61], v[66:67], v[54:55] op_sel_hi:[0,1]
	v_exp_f32_e32 v60, v60
	v_exp_f32_e32 v61, v61
	v_cvt_pk_bf16_f32 v56, v56, v57
	v_cvt_pk_bf16_f32 v57, v58, v59
	v_pk_fma_f32 v[58:59], v[62:63], v[208:209], v[208:209] op_sel_hi:[1,0,0]
	v_pk_mul_f32 v[48:49], v[52:53], v[48:49]
	v_rcp_f32_e32 v58, v58
	v_rcp_f32_e32 v59, v59
	v_pk_fma_f32 v[52:53], v[60:61], v[208:209], v[208:209] op_sel_hi:[1,0,0]
	v_pk_mul_f32 v[50:51], v[54:55], v[50:51]
	v_rcp_f32_e32 v52, v52
	v_rcp_f32_e32 v53, v53
	v_pk_mul_f32 v[48:49], v[58:59], v[48:49]
	v_pk_mul_f32 v[40:41], v[44:45], v[40:41]
	v_cvt_pk_bf16_f32 v58, v48, v49
	v_pk_mul_f32 v[48:49], v[52:53], v[50:51]
	v_fmamk_f32 v50, v161, 0x3a800000, v151
	v_mov_b32_e32 v210, v50
	v_rsq_f32_e32 v51, v50
	v_cvt_pk_bf16_f32 v59, v48, v49
	v_mad_i64_i32 v[48:49], s[18:19], v65, s56, v[112:113]
	v_mul_f32_e32 v50, 0xbfb8aa3b, v51
	v_pk_mul_f32 v[52:53], v[50:51], v[44:45] op_sel_hi:[0,1]
	v_exp_f32_e32 v52, v52
	v_exp_f32_e32 v53, v53
	v_pk_mul_f32 v[44:45], v[50:51], v[46:47] op_sel_hi:[0,1]
	v_exp_f32_e32 v44, v44
	v_exp_f32_e32 v45, v45
	v_pk_fma_f32 v[52:53], v[52:53], v[210:211], v[210:211] op_sel_hi:[1,0,0]
	v_lshl_add_u64 v[48:49], v[48:49], 0, v[114:115]
	v_rcp_f32_e32 v52, v52
	v_rcp_f32_e32 v53, v53
	v_pk_fma_f32 v[44:45], v[44:45], v[210:211], v[210:211] op_sel_hi:[1,0,0]
	global_store_dwordx4 v[48:49], v[56:59], off
	v_rcp_f32_e32 v44, v44
	v_rcp_f32_e32 v45, v45
	v_pk_mul_f32 v[42:43], v[46:47], v[42:43]
	v_pk_mul_f32 v[40:41], v[52:53], v[40:41]
	v_pk_mul_f32 v[46:47], v[50:51], v[36:37] op_sel_hi:[0,1]
	v_exp_f32_e32 v46, v46
	v_exp_f32_e32 v47, v47
	v_pk_mul_f32 v[42:43], v[44:45], v[42:43]
	v_pk_mul_f32 v[44:45], v[50:51], v[38:39] op_sel_hi:[0,1]
	v_exp_f32_e32 v44, v44
	v_exp_f32_e32 v45, v45
	v_cvt_pk_bf16_f32 v40, v40, v41
	v_cvt_pk_bf16_f32 v41, v42, v43
	v_pk_fma_f32 v[42:43], v[46:47], v[210:211], v[210:211] op_sel_hi:[1,0,0]
	v_pk_mul_f32 v[32:33], v[36:37], v[32:33]
	v_rcp_f32_e32 v42, v42
	v_rcp_f32_e32 v43, v43
	v_pk_fma_f32 v[36:37], v[44:45], v[210:211], v[210:211] op_sel_hi:[1,0,0]
	v_pk_mul_f32 v[34:35], v[38:39], v[34:35]
	v_rcp_f32_e32 v36, v36
	v_rcp_f32_e32 v37, v37
	v_pk_mul_f32 v[32:33], v[42:43], v[32:33]
	v_pk_mul_f32 v[24:25], v[28:29], v[24:25]
	v_cvt_pk_bf16_f32 v42, v32, v33
	v_pk_mul_f32 v[32:33], v[36:37], v[34:35]
	v_pk_mul_f32 v[26:27], v[30:31], v[26:27]
	v_cvt_pk_bf16_f32 v43, v32, v33
	v_fmamk_f32 v32, v152, 0x3a800000, v151
	v_mov_b32_e32 v212, v32
	v_rsq_f32_e32 v35, v32
	v_add_u32_e32 v32, 0x90, v144
	v_mad_i64_i32 v[32:33], s[18:19], v32, s56, v[112:113]
	v_mul_f32_e32 v34, 0xbfb8aa3b, v35
	v_pk_mul_f32 v[36:37], v[34:35], v[28:29] op_sel_hi:[0,1]
	v_exp_f32_e32 v36, v36
	v_exp_f32_e32 v37, v37
	v_pk_mul_f32 v[28:29], v[34:35], v[30:31] op_sel_hi:[0,1]
	v_exp_f32_e32 v28, v28
	v_exp_f32_e32 v29, v29
	v_pk_fma_f32 v[36:37], v[36:37], v[212:213], v[212:213] op_sel_hi:[1,0,0]
	v_lshl_add_u64 v[32:33], v[32:33], 0, v[114:115]
	v_rcp_f32_e32 v36, v36
	v_rcp_f32_e32 v37, v37
	v_pk_fma_f32 v[28:29], v[28:29], v[212:213], v[212:213] op_sel_hi:[1,0,0]
	global_store_dwordx4 v[32:33], v[40:43], off
	v_rcp_f32_e32 v28, v28
	v_rcp_f32_e32 v29, v29
	v_pk_mul_f32 v[24:25], v[36:37], v[24:25]
	v_pk_mul_f32 v[30:31], v[34:35], v[20:21] op_sel_hi:[0,1]
	v_exp_f32_e32 v30, v30
	v_exp_f32_e32 v31, v31
	v_pk_mul_f32 v[26:27], v[28:29], v[26:27]
	v_pk_mul_f32 v[28:29], v[34:35], v[22:23] op_sel_hi:[0,1]
	v_exp_f32_e32 v28, v28
	v_exp_f32_e32 v29, v29
	v_cvt_pk_bf16_f32 v24, v24, v25
	v_cvt_pk_bf16_f32 v25, v26, v27
	v_pk_fma_f32 v[26:27], v[30:31], v[212:213], v[212:213] op_sel_hi:[1,0,0]
	v_pk_mul_f32 v[16:17], v[20:21], v[16:17]
	v_rcp_f32_e32 v26, v26
	v_rcp_f32_e32 v27, v27
	v_pk_fma_f32 v[20:21], v[28:29], v[212:213], v[212:213] op_sel_hi:[1,0,0]
	v_pk_mul_f32 v[18:19], v[22:23], v[18:19]
	v_rcp_f32_e32 v20, v20
	v_rcp_f32_e32 v21, v21
	v_pk_mul_f32 v[16:17], v[26:27], v[16:17]
	v_pk_mul_f32 v[8:9], v[12:13], v[8:9]
	v_cvt_pk_bf16_f32 v26, v16, v17
	v_pk_mul_f32 v[16:17], v[20:21], v[18:19]
	v_pk_mul_f32 v[10:11], v[14:15], v[10:11]
	v_cvt_pk_bf16_f32 v27, v16, v17
	v_fmamk_f32 v16, v149, 0x3a800000, v151
	v_mov_b32_e32 v214, v16
	v_rsq_f32_e32 v19, v16
	v_add_u32_e32 v16, 0xa0, v144
	v_mad_i64_i32 v[16:17], s[18:19], v16, s56, v[112:113]
	v_mul_f32_e32 v18, 0xbfb8aa3b, v19
	v_pk_mul_f32 v[20:21], v[18:19], v[12:13] op_sel_hi:[0,1]
	v_exp_f32_e32 v20, v20
	v_exp_f32_e32 v21, v21
	v_pk_mul_f32 v[12:13], v[18:19], v[14:15] op_sel_hi:[0,1]
	v_exp_f32_e32 v12, v12
	v_exp_f32_e32 v13, v13
	v_pk_fma_f32 v[20:21], v[20:21], v[214:215], v[214:215] op_sel_hi:[1,0,0]
	v_lshl_add_u64 v[16:17], v[16:17], 0, v[114:115]
	v_rcp_f32_e32 v20, v20
	v_rcp_f32_e32 v21, v21
	v_pk_fma_f32 v[12:13], v[12:13], v[214:215], v[214:215] op_sel_hi:[1,0,0]
	global_store_dwordx4 v[16:17], v[24:27], off
	v_rcp_f32_e32 v12, v12
	v_rcp_f32_e32 v13, v13
	v_pk_mul_f32 v[8:9], v[20:21], v[8:9]
	v_pk_mul_f32 v[14:15], v[18:19], v[4:5] op_sel_hi:[0,1]
	v_exp_f32_e32 v14, v14
	v_exp_f32_e32 v15, v15
	v_pk_mul_f32 v[10:11], v[12:13], v[10:11]
	v_pk_mul_f32 v[12:13], v[18:19], v[6:7] op_sel_hi:[0,1]
	v_exp_f32_e32 v12, v12
	v_exp_f32_e32 v13, v13
	v_cvt_pk_bf16_f32 v8, v8, v9
	v_cvt_pk_bf16_f32 v9, v10, v11
	v_pk_fma_f32 v[10:11], v[14:15], v[214:215], v[214:215] op_sel_hi:[1,0,0]
	v_pk_mul_f32 v[0:1], v[4:5], v[0:1]
	v_rcp_f32_e32 v10, v10
	v_rcp_f32_e32 v11, v11
	v_pk_fma_f32 v[4:5], v[12:13], v[214:215], v[214:215] op_sel_hi:[1,0,0]
	v_pk_mul_f32 v[2:3], v[6:7], v[2:3]
	v_rcp_f32_e32 v4, v4
	v_rcp_f32_e32 v5, v5
	v_pk_mul_f32 v[0:1], v[10:11], v[0:1]
	s_andn2_b64 vcc, exec, s[0:1]
	v_cvt_pk_bf16_f32 v10, v0, v1
	v_pk_mul_f32 v[0:1], v[4:5], v[2:3]
	s_mov_b64 s[0:1], -1
	v_cvt_pk_bf16_f32 v11, v0, v1
	v_add_u32_e32 v0, 0xb0, v144
	v_mad_i64_i32 v[0:1], s[18:19], v0, s56, v[112:113]
	v_lshl_add_u64 v[0:1], v[0:1], 0, v[114:115]
	global_store_dwordx4 v[0:1], v[8:11], off
	s_cbranch_vccnz .LBB0_681
	s_andn2_b64 vcc, exec, s[6:7]
	s_cbranch_vccnz .LBB0_680
	s_barrier
	s_branch .LBB0_680
